# attention loop: staging->LDS stores moved to mid-iteration and global tile loads issued one full iteration ahead
# speedup vs baseline: 1.0017x; 1.0017x over previous
; #define AT_LOAD(X, t) do { const size_t adv_ = (size_t)(t) * 64; sk##X = *(const u32x4*)(gk + adv_ * 1024); sv##X = *(const u32x4*)(gv + adv_ * 1024); if (rth) sr##X = *(const u32x4*)(gr + adv_ * 32); } while (0)
; __device__ __forceinline__ void attn_unit(LAS char* lds, const bf16_t* Qp, const bf16_t* KVp, const bf16_t* KRp, int ntiles, bf16_t* Yp, bool dry) {
;     ...
;     for (int t = 0; t < ntiles; t += 2) {
;         const int sb0 = (t & 2);
;         const bool more = (t + 2 < ntiles);
;         f32x16 pa0 = {}, pa1 = {}, pb0 = {}, pb1 = {};
;         AT_QK(sb0, pa0, pa1);
;         AT_QK(sb0 + 1, pb0, pb1);
;         if (t == 0) AT_SMPV(sb0, true, pa0, pa1); else AT_SMPV(sb0, false, pa0, pa1);
;         __builtin_amdgcn_sched_barrier(0);
;         if (more) { AT_LOAD(A, t + 2); AT_LOAD(B, t + 3); }
.Latt_iter:
	s_waitcnt vmcnt(0)
	v_xor_b32_e32 v82, 0x80000000, v189
	v_mov_b32_e32 v83, v82
	v_mov_b32_e32 v84, v82
	v_mov_b32_e32 v85, v82
	v_mov_b32_e32 v86, v82
	v_mov_b32_e32 v87, v82
	v_mov_b32_e32 v88, v82
	v_mov_b32_e32 v89, v82
	v_mov_b32_e32 v90, v82
	v_mov_b32_e32 v91, v82
	v_mov_b32_e32 v92, v82
	v_mov_b32_e32 v93, v82
	v_mov_b32_e32 v94, v82
	v_mov_b32_e32 v95, v82
	v_mov_b32_e32 v96, v82
	v_mov_b32_e32 v97, v82
	v_lshl_add_u64 v[178:179], s[88:89], 0, v[194:195]
	v_add_co_u32_e32 v180, vcc, 0x2f440000, v178
	s_nop 1
	v_addc_co_u32_e32 v181, vcc, 0, v179, vcc
	global_load_dwordx4 v[130:133], v[180:181], off
	global_load_dwordx4 v[134:137], v[180:181], off offset:1024
	v_lshl_add_u64 v[180:181], s[88:89], 0, v[192:193]
	s_and_saveexec_b64 s[16:17], s[38:39]
	s_cbranch_execz .Latt_l1i
	v_add_co_u32_e32 v248, vcc, 0x3cc02000, v180
	s_nop 1
	v_addc_co_u32_e32 v249, vcc, 0, v181, vcc
	global_load_dwordx4 v[138:141], v[248:249], off

; #define AT_LOAD(X, t) do { const size_t adv_ = (size_t)(t) * 64; sk##X = *(const u32x4*)(gk + adv_ * 1024); sv##X = *(const u32x4*)(gv + adv_ * 1024); if (rth) sr##X = *(const u32x4*)(gr + adv_ * 32); } while (0)
; #define AT_STORE(X, slot) do { *(LAS u32x4*)(lds + A_K0 + (slot) * AK_BYTES + lk) = sk##X; *(LAS u32x4*)(lds + A_V0 + (slot) * AV_BYTES + lv) = sv##X; if (rth) *(LAS u32x4*)(lds + A_K0 + (slot) * AK_BYTES + lr) = sr##X; } while (0)
; __device__ __forceinline__ void attn_unit(LAS char* lds, const bf16_t* Qp, const bf16_t* KVp, const bf16_t* KRp, int ntiles, bf16_t* Yp, bool dry) {
;     ...
;         if (more) { AT_LOAD(A, t + 2); AT_LOAD(B, t + 3); }
;         AT_SMPV(sb0 + 1, false, pb0, pb1);
;         if (more) { AT_STORE(A, sb0 ^ 2); AT_STORE(B, (sb0 ^ 2) + 1); }
.Latt_noloadi:
.Latt_loop:
	s_and_b32 s42, s35, 2
	s_mul_i32 s2, s42, 0x3400
	v_add_u32_e32 v0, s2, v209
	v_lshl_add_u32 v185, s42, 13, v208
	v_add_u32_e32 v184, 0x2000, v185
	ds_read_b128 v[66:69], v0 offset:0
	ds_read_b128 v[70:73], v0 offset:6656
	ds_read_b128 v[74:77], v0 offset:32
	ds_read_b128 v[78:81], v0 offset:6688
	ds_read_b128 v[212:215], v0 offset:64
	ds_read_b128 v[240:243], v0 offset:6720
	ds_read_b128 v[244:247], v0 offset:96
	s_waitcnt lgkmcnt(6)
	v_mfma_f32_32x32x16_bf16 v[114:129], v[66:69], v[154:157], v[82:97]
	ds_read_b128 v[248:251], v0 offset:6752
	s_waitcnt lgkmcnt(6)
	v_mfma_f32_32x32x16_bf16 v[98:113], v[70:73], v[154:157], v[82:97]
	ds_read_b128 v[66:69], v0 offset:128
	s_waitcnt lgkmcnt(6)
	v_mfma_f32_32x32x16_bf16 v[114:129], v[74:77], v[158:161], v[114:129]
	ds_read_b128 v[70:73], v0 offset:6784
	s_waitcnt lgkmcnt(6)
	v_mfma_f32_32x32x16_bf16 v[98:113], v[78:81], v[158:161], v[98:113]
	ds_read_b128 v[74:77], v0 offset:160
	s_waitcnt lgkmcnt(6)
	v_mfma_f32_32x32x16_bf16 v[114:129], v[212:215], v[162:165], v[114:129]
	ds_read_b128 v[78:81], v0 offset:6816
	s_waitcnt lgkmcnt(6)
	v_mfma_f32_32x32x16_bf16 v[98:113], v[240:243], v[162:165], v[98:113]
	ds_read_b128 v[212:215], v0 offset:13312
	s_waitcnt lgkmcnt(6)
	v_mfma_f32_32x32x16_bf16 v[114:129], v[244:247], v[166:169], v[114:129]
	ds_read_b128 v[240:243], v0 offset:19968
	s_waitcnt lgkmcnt(6)
	v_mfma_f32_32x32x16_bf16 v[98:113], v[248:251], v[166:169], v[98:113]
	ds_read_b128 v[244:247], v0 offset:13344
	s_waitcnt lgkmcnt(6)
	v_mfma_f32_32x32x16_bf16 v[114:129], v[66:69], v[170:173], v[114:129]
	ds_read_b128 v[248:251], v0 offset:20000
	s_waitcnt lgkmcnt(6)
	v_mfma_f32_32x32x16_bf16 v[98:113], v[70:73], v[170:173], v[98:113]
	ds_read_b128 v[66:69], v0 offset:13376
	s_waitcnt lgkmcnt(6)
	v_mfma_f32_32x32x16_bf16 v[114:129], v[74:77], v[174:177], v[114:129]
	ds_read_b128 v[70:73], v0 offset:20032
	s_waitcnt lgkmcnt(6)
	v_mfma_f32_32x32x16_bf16 v[98:113], v[78:81], v[174:177], v[98:113]
	ds_read_b128 v[74:77], v0 offset:13408
	s_waitcnt lgkmcnt(6)
	v_mfma_f32_32x32x16_bf16 v[2:17], v[212:215], v[154:157], v[82:97]
	ds_read_b128 v[78:81], v0 offset:20064
	s_waitcnt lgkmcnt(6)
	v_mfma_f32_32x32x16_bf16 v[18:33], v[240:243], v[154:157], v[82:97]
	ds_read_b128 v[212:215], v0 offset:13440
	s_waitcnt lgkmcnt(6)
	v_mfma_f32_32x32x16_bf16 v[2:17], v[244:247], v[158:161], v[2:17]
	ds_read_b128 v[240:243], v0 offset:20096
	s_waitcnt lgkmcnt(6)
	v_mfma_f32_32x32x16_bf16 v[18:33], v[248:251], v[158:161], v[18:33]
	ds_read_b128 v[244:247], v0 offset:13472
	s_waitcnt lgkmcnt(6)
	v_mfma_f32_32x32x16_bf16 v[2:17], v[66:69], v[162:165], v[2:17]
	ds_read_b128 v[248:251], v0 offset:20128
	s_waitcnt lgkmcnt(6)
	v_mfma_f32_32x32x16_bf16 v[18:33], v[70:73], v[162:165], v[18:33]
	ds_read_b64_tr_b16 v[216:217], v185 offset:53248
	ds_read_b64_tr_b16 v[218:219], v185 offset:53760
	s_waitcnt lgkmcnt(7)
	v_mfma_f32_32x32x16_bf16 v[2:17], v[74:77], v[166:169], v[2:17]
	ds_read_b64_tr_b16 v[220:221], v185 offset:57344
	ds_read_b64_tr_b16 v[222:223], v185 offset:57856
	s_waitcnt lgkmcnt(8)
	v_mfma_f32_32x32x16_bf16 v[18:33], v[78:81], v[166:169], v[18:33]
	ds_read_b64_tr_b16 v[224:225], v185 offset:54272
	ds_read_b64_tr_b16 v[226:227], v185 offset:54784
	s_waitcnt lgkmcnt(9)
	v_mfma_f32_32x32x16_bf16 v[2:17], v[212:215], v[170:173], v[2:17]
	ds_read_b64_tr_b16 v[228:229], v185 offset:58368
	ds_read_b64_tr_b16 v[230:231], v185 offset:58880
	s_waitcnt lgkmcnt(10)
	v_mfma_f32_32x32x16_bf16 v[18:33], v[240:243], v[170:173], v[18:33]
	ds_read_b64_tr_b16 v[232:233], v185 offset:55296
	ds_read_b64_tr_b16 v[234:235], v185 offset:55808
	s_waitcnt lgkmcnt(11)
	v_mfma_f32_32x32x16_bf16 v[2:17], v[244:247], v[174:177], v[2:17]
	ds_read_b64_tr_b16 v[236:237], v185 offset:59392
	ds_read_b64_tr_b16 v[238:239], v185 offset:59904
	s_waitcnt lgkmcnt(12)
	v_mfma_f32_32x32x16_bf16 v[18:33], v[248:251], v[174:177], v[18:33]
	s_waitcnt lgkmcnt(7)
	s_cmp_gt_u32 s35, 33
	s_cbranch_scc1 .Latt_stdone
	s_xor_b32 s14, s42, 2
	s_mul_i32 s17, s14, 0x3400
	s_add_i32 s16, s17, 0
	v_add_u32_e32 v212, s16, v190
	s_waitcnt vmcnt(3)
	ds_write_b128 v212, v[130:133]
	v_lshl_add_u32 v212, s14, 13, v201
	s_waitcnt vmcnt(2)
	ds_write_b128 v212, v[134:137] offset:53248
	s_and_saveexec_b64 s[14:15], s[0:1]
	s_xor_b64 s[14:15], exec, s[14:15]
	s_cbranch_execz .Latt_st1
	v_add_u32_e32 v213, s17, v200
	s_waitcnt vmcnt(1)
	ds_write_b128 v213, v[146:149] offset:13312
	s_waitcnt vmcnt(0)
	ds_write_b128 v212, v[150:153] offset:61440
.Latt_st1:
	s_andn2_saveexec_b64 s[14:15], s[14:15]
	s_cbranch_execz .Latt_st2
	v_add_u32_e32 v213, s16, v206
	s_addk_i32 s16, 0x3400
	ds_write_b128 v213, v[138:141] offset:128
	v_add_u32_e32 v213, s16, v190
	s_waitcnt vmcnt(1)
	ds_write_b128 v213, v[146:149]
	s_waitcnt vmcnt(0)
	ds_write_b128 v212, v[150:153] offset:61440
	v_add_u32_e32 v212, s16, v206
	ds_write_b128 v212, v[142:145] offset:128
.Latt_st2:
	s_or_b64 exec, exec, s[14:15]
	v_lshl_add_u64 v[192:193], v[192:193], 0, s[60:61]
	v_lshl_add_u64 v[194:195], v[194:195], 0, s[26:27]
	s_cmp_gt_u32 s35, 31
	s_cbranch_scc1 .Latt_noloadm
	v_lshl_add_u64 v[178:179], s[88:89], 0, v[194:195]
	v_add_co_u32_e32 v180, vcc, 0x2f440000, v178
	s_nop 1
	v_addc_co_u32_e32 v181, vcc, 0, v179, vcc
	global_load_dwordx4 v[130:133], v[180:181], off
	global_load_dwordx4 v[134:137], v[180:181], off offset:1024
	v_lshl_add_u64 v[180:181], s[88:89], 0, v[192:193]
	s_and_saveexec_b64 s[16:17], s[38:39]
	s_cbranch_execz .Latt_l1m
	v_add_co_u32_e32 v248, vcc, 0x3cc02000, v180
	s_nop 1
	v_addc_co_u32_e32 v249, vcc, 0, v181, vcc
	global_load_dwordx4 v[138:141], v[248:249], off

.Latt_noloadm:
.Latt_stdone:
	v_exp_f32_e32 v114, v114
	v_exp_f32_e32 v115, v115
	v_exp_f32_e32 v116, v116
	v_exp_f32_e32 v117, v117
	v_exp_f32_e32 v118, v118
	v_exp_f32_e32 v119, v119
	v_exp_f32_e32 v120, v120
	v_exp_f32_e32 v121, v121
	v_cvt_pk_bf16_f32 v66, v114, v115
	v_cvt_pk_bf16_f32 v67, v116, v117
	v_cvt_pk_bf16_f32 v68, v118, v119
	v_cvt_pk_bf16_f32 v69, v120, v121
	v_add_f32_e32 v178, v114, v115
	v_add_f32_e32 v179, v116, v117
	v_add_f32_e32 v180, v118, v119
	v_add_f32_e32 v181, v120, v121
	v_add_f32_e32 v178, v178, v179
	v_add_f32_e32 v180, v180, v181
	v_add_f32_e32 v178, v178, v180
	v_add_f32_e32 v210, v210, v178
	s_waitcnt lgkmcnt(11)
	ds_read_b64_tr_b16 v[240:241], v185 offset:56320
	ds_read_b64_tr_b16 v[242:243], v185 offset:56832
	ds_read_b64_tr_b16 v[244:245], v185 offset:60416
	ds_read_b64_tr_b16 v[246:247], v185 offset:60928
	s_waitcnt lgkmcnt(11)
	ds_read_b64_tr_b16 v[114:115], v184 offset:53248
	ds_read_b64_tr_b16 v[116:117], v184 offset:53760
	ds_read_b64_tr_b16 v[118:119], v184 offset:57344
	ds_read_b64_tr_b16 v[120:121], v184 offset:57856
	v_exp_f32_e32 v122, v122
	v_exp_f32_e32 v123, v123
	v_exp_f32_e32 v124, v124
	v_mfma_f32_32x32x16_bf16 v[34:49], v[66:69], v[216:219], v[34:49]
	v_exp_f32_e32 v125, v125
	v_exp_f32_e32 v126, v126
	v_exp_f32_e32 v127, v127
	v_exp_f32_e32 v128, v128
	v_exp_f32_e32 v129, v129
	v_cvt_pk_bf16_f32 v70, v122, v123
	v_cvt_pk_bf16_f32 v71, v124, v125
	v_mfma_f32_32x32x16_bf16 v[50:65], v[66:69], v[220:223], v[50:65]
	v_cvt_pk_bf16_f32 v72, v126, v127
	v_cvt_pk_bf16_f32 v73, v128, v129
	v_add_f32_e32 v178, v122, v123
	v_add_f32_e32 v179, v124, v125
	v_add_f32_e32 v180, v126, v127
	v_add_f32_e32 v181, v128, v129
	v_add_f32_e32 v178, v178, v179
	v_add_f32_e32 v180, v180, v181
	v_add_f32_e32 v178, v178, v180
	v_add_f32_e32 v210, v210, v178
	s_waitcnt lgkmcnt(11)
	ds_read_b64_tr_b16 v[122:123], v184 offset:54272
	ds_read_b64_tr_b16 v[124:125], v184 offset:54784
	ds_read_b64_tr_b16 v[126:127], v184 offset:58368
	ds_read_b64_tr_b16 v[128:129], v184 offset:58880
	v_exp_f32_e32 v98, v98
	v_exp_f32_e32 v99, v99
	v_exp_f32_e32 v100, v100
	v_mfma_f32_32x32x16_bf16 v[34:49], v[70:73], v[224:227], v[34:49]
	v_exp_f32_e32 v101, v101
	v_exp_f32_e32 v102, v102
	v_exp_f32_e32 v103, v103
	v_exp_f32_e32 v104, v104
	v_exp_f32_e32 v105, v105
	v_cvt_pk_bf16_f32 v74, v98, v99
	v_cvt_pk_bf16_f32 v75, v100, v101
	v_mfma_f32_32x32x16_bf16 v[50:65], v[70:73], v[228:231], v[50:65]
	v_cvt_pk_bf16_f32 v76, v102, v103
	v_cvt_pk_bf16_f32 v77, v104, v105
	v_add_f32_e32 v178, v98, v99
	v_add_f32_e32 v179, v100, v101
	v_add_f32_e32 v180, v102, v103
	v_add_f32_e32 v181, v104, v105
	v_add_f32_e32 v178, v178, v179
	v_add_f32_e32 v180, v180, v181
	v_add_f32_e32 v178, v178, v180
	v_add_f32_e32 v210, v210, v178
	s_waitcnt lgkmcnt(11)
	ds_read_b64_tr_b16 v[98:99], v184 offset:55296
	ds_read_b64_tr_b16 v[100:101], v184 offset:55808
	ds_read_b64_tr_b16 v[102:103], v184 offset:59392
	ds_read_b64_tr_b16 v[104:105], v184 offset:59904
	v_exp_f32_e32 v106, v106
	v_exp_f32_e32 v107, v107
	v_exp_f32_e32 v108, v108
	v_mfma_f32_32x32x16_bf16 v[34:49], v[74:77], v[232:235], v[34:49]
	v_exp_f32_e32 v109, v109
	v_exp_f32_e32 v110, v110
	v_exp_f32_e32 v111, v111
	v_exp_f32_e32 v112, v112
	v_exp_f32_e32 v113, v113
	v_cvt_pk_bf16_f32 v78, v106, v107
	v_cvt_pk_bf16_f32 v79, v108, v109
	v_mfma_f32_32x32x16_bf16 v[50:65], v[74:77], v[236:239], v[50:65]
	v_cvt_pk_bf16_f32 v80, v110, v111
	v_cvt_pk_bf16_f32 v81, v112, v113
	v_add_f32_e32 v178, v106, v107
	v_add_f32_e32 v179, v108, v109
	v_add_f32_e32 v180, v110, v111
	v_add_f32_e32 v181, v112, v113
	v_add_f32_e32 v178, v178, v179
	v_add_f32_e32 v180, v180, v181
	v_add_f32_e32 v178, v178, v180
	v_add_f32_e32 v210, v210, v178
	s_waitcnt lgkmcnt(11)
; #define AT_LOAD(X, t) do { const size_t adv_ = (size_t)(t) * 64; sk##X = *(const u32x4*)(gk + adv_ * 1024); sv##X = *(const u32x4*)(gv + adv_ * 1024); if (rth) sr##X = *(const u32x4*)(gr + adv_ * 32); } while (0)
; #define AT_STORE(X, slot) do { *(LAS u32x4*)(lds + A_K0 + (slot) * AK_BYTES + lk) = sk##X; *(LAS u32x4*)(lds + A_V0 + (slot) * AV_BYTES + lv) = sv##X; if (rth) *(LAS u32x4*)(lds + A_K0 + (slot) * AK_BYTES + lr) = sr##X; } while (0)
; __device__ __forceinline__ void attn_unit(LAS char* lds, const bf16_t* Qp, const bf16_t* KVp, const bf16_t* KRp, int ntiles, bf16_t* Yp, bool dry) {
;     ...
;     for (int t = 0; t < ntiles; t += 2) {
;         const int sb0 = (t & 2);
;         const bool more = (t + 2 < ntiles);
;         f32x16 pa0 = {}, pa1 = {}, pb0 = {}, pb1 = {};
;         AT_QK(sb0, pa0, pa1);
;         AT_QK(sb0 + 1, pb0, pb1);
;         if (t == 0) AT_SMPV(sb0, true, pa0, pa1); else AT_SMPV(sb0, false, pa0, pa1);
;         __builtin_amdgcn_sched_barrier(0);
;         if (more) { AT_LOAD(A, t + 2); AT_LOAD(B, t + 3); }
;         AT_SMPV(sb0 + 1, false, pb0, pb1);
;         if (more) { AT_STORE(A, sb0 ^ 2); AT_STORE(B, (sb0 ^ 2) + 1); }
;         __syncthreads();
;     }
	ds_read_b64_tr_b16 v[106:107], v184 offset:56320
	ds_read_b64_tr_b16 v[108:109], v184 offset:56832
	ds_read_b64_tr_b16 v[110:111], v184 offset:60416
	ds_read_b64_tr_b16 v[112:113], v184 offset:60928
	v_exp_f32_e32 v2, v2
	v_exp_f32_e32 v3, v3
	v_exp_f32_e32 v4, v4
	v_mfma_f32_32x32x16_bf16 v[34:49], v[78:81], v[240:243], v[34:49]
	v_exp_f32_e32 v5, v5
	v_exp_f32_e32 v6, v6
	v_exp_f32_e32 v7, v7
	v_exp_f32_e32 v8, v8
	v_exp_f32_e32 v9, v9
	v_cvt_pk_bf16_f32 v66, v2, v3
	v_cvt_pk_bf16_f32 v67, v4, v5
	v_mfma_f32_32x32x16_bf16 v[50:65], v[78:81], v[244:247], v[50:65]
	v_cvt_pk_bf16_f32 v68, v6, v7
	v_cvt_pk_bf16_f32 v69, v8, v9
	v_add_f32_e32 v178, v2, v3
	v_add_f32_e32 v179, v4, v5
	v_add_f32_e32 v180, v6, v7
	v_add_f32_e32 v181, v8, v9
	v_add_f32_e32 v178, v178, v179
	v_add_f32_e32 v180, v180, v181
	v_add_f32_e32 v178, v178, v180
	v_add_f32_e32 v210, v210, v178
	v_exp_f32_e32 v10, v10
	v_exp_f32_e32 v11, v11
	v_exp_f32_e32 v12, v12
	s_waitcnt lgkmcnt(14)
	v_mfma_f32_32x32x16_bf16 v[34:49], v[66:69], v[114:117], v[34:49]
	v_exp_f32_e32 v13, v13
	v_exp_f32_e32 v14, v14
	v_exp_f32_e32 v15, v15
	v_exp_f32_e32 v16, v16
	v_exp_f32_e32 v17, v17
	v_cvt_pk_bf16_f32 v70, v10, v11
	v_cvt_pk_bf16_f32 v71, v12, v13
	s_waitcnt lgkmcnt(12)
	v_mfma_f32_32x32x16_bf16 v[50:65], v[66:69], v[118:121], v[50:65]
	v_cvt_pk_bf16_f32 v72, v14, v15
	v_cvt_pk_bf16_f32 v73, v16, v17
	v_add_f32_e32 v178, v10, v11
	v_add_f32_e32 v179, v12, v13
	v_add_f32_e32 v180, v14, v15
	v_add_f32_e32 v181, v16, v17
	v_add_f32_e32 v178, v178, v179
	v_add_f32_e32 v180, v180, v181
	v_add_f32_e32 v178, v178, v180
	v_add_f32_e32 v210, v210, v178
	v_exp_f32_e32 v18, v18
	v_exp_f32_e32 v19, v19
	v_exp_f32_e32 v20, v20
	s_waitcnt lgkmcnt(10)
	v_mfma_f32_32x32x16_bf16 v[34:49], v[70:73], v[122:125], v[34:49]
	v_exp_f32_e32 v21, v21
	v_exp_f32_e32 v22, v22
	v_exp_f32_e32 v23, v23
	v_exp_f32_e32 v24, v24
	v_exp_f32_e32 v25, v25
	v_cvt_pk_bf16_f32 v74, v18, v19
	v_cvt_pk_bf16_f32 v75, v20, v21
	s_waitcnt lgkmcnt(8)
	v_mfma_f32_32x32x16_bf16 v[50:65], v[70:73], v[126:129], v[50:65]
	v_cvt_pk_bf16_f32 v76, v22, v23
	v_cvt_pk_bf16_f32 v77, v24, v25
	v_add_f32_e32 v178, v18, v19
	v_add_f32_e32 v179, v20, v21
	v_add_f32_e32 v180, v22, v23
	v_add_f32_e32 v181, v24, v25
	v_add_f32_e32 v178, v178, v179
	v_add_f32_e32 v180, v180, v181
	v_add_f32_e32 v178, v178, v180
	v_add_f32_e32 v210, v210, v178
	v_exp_f32_e32 v26, v26
	v_exp_f32_e32 v27, v27
	v_exp_f32_e32 v28, v28
	s_waitcnt lgkmcnt(6)
	v_mfma_f32_32x32x16_bf16 v[34:49], v[74:77], v[98:101], v[34:49]
	v_exp_f32_e32 v29, v29
	v_exp_f32_e32 v30, v30
	v_exp_f32_e32 v31, v31
	v_exp_f32_e32 v32, v32
	v_exp_f32_e32 v33, v33
	v_cvt_pk_bf16_f32 v78, v26, v27
	v_cvt_pk_bf16_f32 v79, v28, v29
	s_waitcnt lgkmcnt(4)
	v_mfma_f32_32x32x16_bf16 v[50:65], v[74:77], v[102:105], v[50:65]
	v_cvt_pk_bf16_f32 v80, v30, v31
	v_cvt_pk_bf16_f32 v81, v32, v33
	v_add_f32_e32 v178, v26, v27
	v_add_f32_e32 v179, v28, v29
	v_add_f32_e32 v180, v30, v31
	v_add_f32_e32 v181, v32, v33
	v_add_f32_e32 v178, v178, v179
	v_add_f32_e32 v180, v180, v181
	v_add_f32_e32 v178, v178, v180
	v_add_f32_e32 v210, v210, v178
	s_waitcnt lgkmcnt(2)
	v_mfma_f32_32x32x16_bf16 v[34:49], v[78:81], v[106:109], v[34:49]
	s_waitcnt lgkmcnt(0)
	v_mfma_f32_32x32x16_bf16 v[50:65], v[78:81], v[110:113], v[50:65]
	s_cmp_eq_u32 s35, 0
	s_cbranch_scc1 .Latt_rs
	v_cmp_lt_f32_e32 vcc, 0x4b800000, v210
	s_cbranch_vccnz .Latt_rs
.Latt_rsback:
.Latt_latch:
	s_add_i32 s35, s35, 2
	s_waitcnt lgkmcnt(0)
	s_barrier
	s_cmp_lt_u32 s35, 36
	s_cbranch_scc1 .Latt_loop
	v_and_b32_e32 v3, 64, v203
	v_xor_b32_e32 v2, 32, v203
	v_add_u32_e32 v3, 64, v3
	v_cmp_lt_i32_e32 vcc, v2, v3
	s_nop 1
	v_cndmask_b32_e32 v2, v203, v2, vcc
	v_lshlrev_b32_e32 v98, 2, v2
	s_branch .LBB0_858
